# GEMM k-loop: 8 redundant s_waitcnt lgkmcnt(0) after the phase barrier removed (the same wait already precedes the barrier, no LDS op in between)
# speedup vs baseline: 1.0087x; 1.0087x over previous
; #define PG8_STAGE(bufoff, gbase, voff) do { _Pragma("unroll") for (int _i = 0; _i < 2; ++_i) \
;         __builtin_amdgcn_global_load_lds((const unsigned*)((const char*)(gbase) + (voff)[_i]), (LAS unsigned*)(lds + (bufoff) + ldsw + _i * 8192), 16, 0, 0); } while (0)
; #define PG8_LDA(dst, b, h) do { _Pragma("unroll") for (int m = 0; m < 4; ++m) _Pragma("unroll") for (int k = 0; k < 2; ++k) dst[m][k] = *(const LAS bf16x8*)(lds + PG8_SA(b, h) + aoff + m * 2048 + k * 1024); } while (0)
; #define PG8_LDB(dst, b, h) do { _Pragma("unroll") for (int n = 0; n < 2; ++n) _Pragma("unroll") for (int k = 0; k < 2; ++k) dst[n][k] = *(const LAS bf16x8*)(lds + PG8_SB(b, h) + boff + n * 2048 + k * 1024); } while (0)
; #define PG8_MMA(ai, bj, At, Bt) do { __builtin_amdgcn_s_setprio(1); _Pragma("unroll") for (int m = 0; m < 4; ++m) _Pragma("unroll") for (int n = 0; n < 2; ++n) _Pragma("unroll") for (int k = 0; k < 2; ++k) \
;         acc[ai][bj][m][n] = __builtin_amdgcn_mfma_f32_16x16x32_bf16(Bt[n][k], At[m][k], acc[ai][bj][m][n], 0, 0, 0); __builtin_amdgcn_s_setprio(0); } while (0)
; #define PG8_WAIT_V(n) asm volatile("s_waitcnt vmcnt(" #n ")" ::: "memory")
; #define PG8_WAIT_L(n) asm volatile("s_waitcnt lgkmcnt(" #n ")" ::: "memory")
; #define PG8_BAR __builtin_amdgcn_s_barrier()
; #define PG8_SCHED __builtin_amdgcn_sched_barrier(0)
; __device__ __forceinline__ void gemm_generic(LAS unsigned char* lds, const GDesc& d, int G, int bx) {
;     ...
;             PG8_LDB(B0, 0, 0); PG8_LDB(B1, 0, 1); PG8_SCHED; PG8_LDA(At, 0, 0); PG8_STAGE(PG8_SA(1, 1), a1 + hstepA, voffA);
;             PG8_WAIT_V(8); PG8_WAIT_L(0); PG8_BAR; PG8_MMA(0, 0, At, B0); PG8_MMA(0, 1, At, B1); PG8_BAR; PG8_SCHED;
;             PG8_LDA(At, 0, 1); PG8_STAGE(PG8_SB(0, 0), b2, voffB); PG8_STAGE(PG8_SB(0, 1), b2 + hstepB, voffB); PG8_STAGE(PG8_SA(0, 0), a2, voffA);
;             PG8_WAIT_V(8); PG8_WAIT_L(0); PG8_BAR; PG8_MMA(1, 0, At, B0); PG8_MMA(1, 1, At, B1); PG8_BAR; PG8_SCHED;
.LBB0_253:
	s_and_b64 s[44:45], exec, s[44:45]
	s_cselect_b32 s45, s83, s16
	s_cselect_b32 s44, s82, s15
	s_nop 0
	s_nop 0
	s_nop 0
	s_nop 0
	s_nop 0
	s_nop 0
	s_nop 0
	s_nop 0
	s_nop 0
	ds_read_b128 v[130:133], v250
	ds_read_b128 v[134:137], v250 offset:1024
	ds_read_b128 v[138:141], v250 offset:2048
	ds_read_b128 v[142:145], v250 offset:3072
	ds_read_b128 v[146:149], v251
	ds_read_b128 v[150:153], v251 offset:1024
	ds_read_b128 v[154:157], v251 offset:2048
	ds_read_b128 v[158:161], v251 offset:3072
	s_add_u32 s34, s12, s34
	s_addc_u32 s35, s13, s35
	s_add_i32 m0, s97, 0xc000
	ds_read_b128 v[162:165], v232
	ds_read_b128 v[166:169], v232 offset:1024
	ds_read_b128 v[170:173], v232 offset:2048
	ds_read_b128 v[174:177], v232 offset:3072
	ds_read_b128 v[178:181], v232 offset:4096
	ds_read_b128 v[182:185], v232 offset:5120
	ds_read_b128 v[186:189], v232 offset:6144
	ds_read_b128 v[190:193], v232 offset:7168
	global_load_lds_dwordx4 v198, s[34:35]
	s_add_i32 m0, s97, 0xe000
	s_nop 0
	global_load_lds_dwordx4 v202, s[34:35]
	s_waitcnt vmcnt(8)
	s_waitcnt lgkmcnt(0)
	s_barrier
	s_setprio 1
	v_mfma_f32_16x16x32_bf16 v[124:127], v[130:133], v[162:165], 0
	v_mfma_f32_16x16x32_bf16 v[120:123], v[138:141], v[162:165], 0
	v_mfma_f32_16x16x32_bf16 v[112:115], v[130:133], v[170:173], 0
	v_mfma_f32_16x16x32_bf16 v[104:107], v[138:141], v[170:173], 0
	v_mfma_f32_16x16x32_bf16 v[96:99], v[130:133], v[178:181], 0
	v_mfma_f32_16x16x32_bf16 v[88:91], v[138:141], v[178:181], 0
	v_mfma_f32_16x16x32_bf16 v[80:83], v[130:133], v[186:189], 0
	v_mfma_f32_16x16x32_bf16 v[72:75], v[138:141], v[186:189], 0
	v_mfma_f32_16x16x32_bf16 v[124:127], v[134:137], v[166:169], v[124:127]
	v_mfma_f32_16x16x32_bf16 v[120:123], v[142:145], v[166:169], v[120:123]
	v_mfma_f32_16x16x32_bf16 v[112:115], v[134:137], v[174:177], v[112:115]
	v_mfma_f32_16x16x32_bf16 v[104:107], v[142:145], v[174:177], v[104:107]
	v_mfma_f32_16x16x32_bf16 v[96:99], v[134:137], v[182:185], v[96:99]
	v_mfma_f32_16x16x32_bf16 v[88:91], v[142:145], v[182:185], v[88:91]
	v_mfma_f32_16x16x32_bf16 v[80:83], v[134:137], v[190:193], v[80:83]
	v_mfma_f32_16x16x32_bf16 v[72:75], v[142:145], v[190:193], v[72:75]
	s_setprio 0
	s_setprio 1
	v_mfma_f32_16x16x32_bf16 v[116:119], v[146:149], v[162:165], 0
	v_mfma_f32_16x16x32_bf16 v[108:111], v[154:157], v[162:165], 0
	v_mfma_f32_16x16x32_bf16 v[100:103], v[146:149], v[170:173], 0
	v_mfma_f32_16x16x32_bf16 v[92:95], v[154:157], v[170:173], 0
	v_mfma_f32_16x16x32_bf16 v[84:87], v[146:149], v[178:181], 0
	v_mfma_f32_16x16x32_bf16 v[76:79], v[154:157], v[178:181], 0
	v_mfma_f32_16x16x32_bf16 v[68:71], v[146:149], v[186:189], 0
	v_mfma_f32_16x16x32_bf16 v[64:67], v[154:157], v[186:189], 0
	v_mfma_f32_16x16x32_bf16 v[116:119], v[150:153], v[166:169], v[116:119]
	v_mfma_f32_16x16x32_bf16 v[108:111], v[158:161], v[166:169], v[108:111]
	v_mfma_f32_16x16x32_bf16 v[100:103], v[150:153], v[174:177], v[100:103]
	v_mfma_f32_16x16x32_bf16 v[92:95], v[158:161], v[174:177], v[92:95]
	v_mfma_f32_16x16x32_bf16 v[84:87], v[150:153], v[182:185], v[84:87]
	v_mfma_f32_16x16x32_bf16 v[76:79], v[158:161], v[182:185], v[76:79]
	v_mfma_f32_16x16x32_bf16 v[68:71], v[150:153], v[190:193], v[68:71]
	v_mfma_f32_16x16x32_bf16 v[64:67], v[158:161], v[190:193], v[64:67]
	s_setprio 0
	s_barrier
	s_add_i32 m0, s95, 0x10000
	ds_read_b128 v[162:165], v232 offset:16384
	ds_read_b128 v[166:169], v232 offset:17408
	ds_read_b128 v[170:173], v232 offset:18432
	ds_read_b128 v[174:177], v232 offset:19456
	ds_read_b128 v[178:181], v232 offset:20480
	ds_read_b128 v[182:185], v232 offset:21504
	ds_read_b128 v[186:189], v232 offset:22528
	ds_read_b128 v[190:193], v232 offset:23552
	global_load_lds_dwordx4 v200, s[44:45]
	s_add_i32 m0, s95, 0x12000
	s_add_u32 s34, s44, s76
	s_addc_u32 s35, s45, s77
	global_load_lds_dwordx4 v204, s[44:45]
	s_add_i32 m0, s95, 0x14000
	s_nop 0
	global_load_lds_dwordx4 v200, s[34:35]
	s_add_i32 m0, s95, 0x16000
	s_nop 0
	global_load_lds_dwordx4 v204, s[34:35]
	s_mov_b32 m0, s97
	s_nop 0
	global_load_lds_dwordx4 v198, s[28:29]
	s_mov_b32 m0, s27
	s_nop 0
	global_load_lds_dwordx4 v202, s[28:29]
	s_waitcnt vmcnt(8)
	s_waitcnt lgkmcnt(0)
	s_barrier
	s_setprio 1
	v_mfma_f32_16x16x32_bf16 v[60:63], v[130:133], v[162:165], 0
	v_mfma_f32_16x16x32_bf16 v[56:59], v[138:141], v[162:165], 0
	v_mfma_f32_16x16x32_bf16 v[48:51], v[130:133], v[170:173], 0
	v_mfma_f32_16x16x32_bf16 v[40:43], v[138:141], v[170:173], 0
	v_mfma_f32_16x16x32_bf16 v[32:35], v[130:133], v[178:181], 0
	v_mfma_f32_16x16x32_bf16 v[24:27], v[138:141], v[178:181], 0
	v_mfma_f32_16x16x32_bf16 v[16:19], v[130:133], v[186:189], 0
	v_mfma_f32_16x16x32_bf16 v[8:11], v[138:141], v[186:189], 0
	v_mfma_f32_16x16x32_bf16 v[60:63], v[134:137], v[166:169], v[60:63]
	v_mfma_f32_16x16x32_bf16 v[56:59], v[142:145], v[166:169], v[56:59]
	v_mfma_f32_16x16x32_bf16 v[48:51], v[134:137], v[174:177], v[48:51]
	v_mfma_f32_16x16x32_bf16 v[40:43], v[142:145], v[174:177], v[40:43]
	v_mfma_f32_16x16x32_bf16 v[32:35], v[134:137], v[182:185], v[32:35]
	v_mfma_f32_16x16x32_bf16 v[24:27], v[142:145], v[182:185], v[24:27]
	v_mfma_f32_16x16x32_bf16 v[16:19], v[134:137], v[190:193], v[16:19]
	v_mfma_f32_16x16x32_bf16 v[8:11], v[142:145], v[190:193], v[8:11]
	s_setprio 0
	s_setprio 1
	v_mfma_f32_16x16x32_bf16 v[52:55], v[146:149], v[162:165], 0
	v_mfma_f32_16x16x32_bf16 v[44:47], v[154:157], v[162:165], 0
	v_mfma_f32_16x16x32_bf16 v[36:39], v[146:149], v[170:173], 0
	v_mfma_f32_16x16x32_bf16 v[28:31], v[154:157], v[170:173], 0
	v_mfma_f32_16x16x32_bf16 v[20:23], v[146:149], v[178:181], 0
	v_mfma_f32_16x16x32_bf16 v[12:15], v[154:157], v[178:181], 0
	v_mfma_f32_16x16x32_bf16 v[4:7], v[146:149], v[186:189], 0
	v_mfma_f32_16x16x32_bf16 v[0:3], v[154:157], v[186:189], 0
	v_mfma_f32_16x16x32_bf16 v[52:55], v[150:153], v[166:169], v[52:55]
	v_mfma_f32_16x16x32_bf16 v[44:47], v[158:161], v[166:169], v[44:47]
	v_mfma_f32_16x16x32_bf16 v[36:39], v[150:153], v[174:177], v[36:39]
	v_mfma_f32_16x16x32_bf16 v[28:31], v[158:161], v[174:177], v[28:31]
	v_mfma_f32_16x16x32_bf16 v[20:23], v[150:153], v[182:185], v[20:23]
	v_mfma_f32_16x16x32_bf16 v[12:15], v[158:161], v[182:185], v[12:15]
	v_mfma_f32_16x16x32_bf16 v[4:7], v[150:153], v[190:193], v[4:7]
	v_mfma_f32_16x16x32_bf16 v[0:3], v[158:161], v[190:193], v[0:3]
	s_setprio 0
	s_barrier
; #define PG8_STAGE(bufoff, gbase, voff) do { _Pragma("unroll") for (int _i = 0; _i < 2; ++_i) \
;         __builtin_amdgcn_global_load_lds((const unsigned*)((const char*)(gbase) + (voff)[_i]), (LAS unsigned*)(lds + (bufoff) + ldsw + _i * 8192), 16, 0, 0); } while (0)
; #define PG8_LDA(dst, b, h) do { _Pragma("unroll") for (int m = 0; m < 4; ++m) _Pragma("unroll") for (int k = 0; k < 2; ++k) dst[m][k] = *(const LAS bf16x8*)(lds + PG8_SA(b, h) + aoff + m * 2048 + k * 1024); } while (0)
; #define PG8_LDB(dst, b, h) do { _Pragma("unroll") for (int n = 0; n < 2; ++n) _Pragma("unroll") for (int k = 0; k < 2; ++k) dst[n][k] = *(const LAS bf16x8*)(lds + PG8_SB(b, h) + boff + n * 2048 + k * 1024); } while (0)
; #define PG8_MMA(ai, bj, At, Bt) do { __builtin_amdgcn_s_setprio(1); _Pragma("unroll") for (int m = 0; m < 4; ++m) _Pragma("unroll") for (int n = 0; n < 2; ++n) _Pragma("unroll") for (int k = 0; k < 2; ++k) \
;         acc[ai][bj][m][n] = __builtin_amdgcn_mfma_f32_16x16x32_bf16(Bt[n][k], At[m][k], acc[ai][bj][m][n], 0, 0, 0); __builtin_amdgcn_s_setprio(0); } while (0)
; #define PG8_WAIT_V(n) asm volatile("s_waitcnt vmcnt(" #n ")" ::: "memory")
; #define PG8_WAIT_L(n) asm volatile("s_waitcnt lgkmcnt(" #n ")" ::: "memory")
; #define PG8_BAR __builtin_amdgcn_s_barrier()
; #define PG8_SCHED __builtin_amdgcn_sched_barrier(0)
; __device__ __forceinline__ void gemm_generic(LAS unsigned char* lds, const GDesc& d, int G, int bx) {
;     ...
;             const char* a1 = cA + a_koff(d, t + 1);
;             const char* a2 = last ? nA : cA + a_koff(d, t + 2); const char* b2 = last ? nB : cB + (size_t)(t + 2) * kstep;
;             const char* a3 = last ? nA + a_koff(d, 1) : cA + a_koff(d, t + 3); const char* b3 = b2 + kstep;
;     ...
;             PG8_LDB(B0, 1, 0); PG8_LDB(B1, 1, 1); PG8_SCHED; PG8_LDA(At, 1, 0); PG8_STAGE(PG8_SA(0, 1), a2 + hstepA, voffA);
;             PG8_WAIT_V(8); PG8_WAIT_L(0); PG8_BAR; PG8_MMA(0, 0, At, B0); PG8_MMA(0, 1, At, B1); PG8_BAR; PG8_SCHED;
;             PG8_LDA(At, 1, 1); PG8_STAGE(PG8_SB(1, 0), b3, voffB); PG8_STAGE(PG8_SB(1, 1), b3 + hstepB, voffB); PG8_STAGE(PG8_SA(1, 0), a3, voffA);
	s_add_i32 s26, 0, 0x1c000
	ds_read_b128 v[130:133], v252
	ds_read_b128 v[134:137], v252 offset:1024
	ds_read_b128 v[138:141], v252 offset:2048
	ds_read_b128 v[142:145], v252 offset:3072
	ds_read_b128 v[146:149], v253
	ds_read_b128 v[150:153], v253 offset:1024
	ds_read_b128 v[154:157], v253 offset:2048
	ds_read_b128 v[158:161], v253 offset:3072
	s_add_u32 s28, s28, s74
	s_addc_u32 s29, s29, s75
	s_mov_b32 m0, s64
	ds_read_b128 v[162:165], v232 offset:32768
	ds_read_b128 v[166:169], v232 offset:33792
	ds_read_b128 v[170:173], v232 offset:34816
	ds_read_b128 v[174:177], v232 offset:35840
	ds_read_b128 v[178:181], v232 offset:36864
	ds_read_b128 v[182:185], v232 offset:37888
	ds_read_b128 v[186:189], v232 offset:38912
	ds_read_b128 v[190:193], v232 offset:39936
	global_load_lds_dwordx4 v198, s[28:29]
	s_mov_b32 m0, s65
	s_nop 0
	global_load_lds_dwordx4 v202, s[28:29]
	s_waitcnt vmcnt(8)
	s_waitcnt lgkmcnt(0)
	s_barrier
	s_setprio 1
	v_mfma_f32_16x16x32_bf16 v[124:127], v[130:133], v[162:165], v[124:127]
	v_mfma_f32_16x16x32_bf16 v[120:123], v[138:141], v[162:165], v[120:123]
	v_mfma_f32_16x16x32_bf16 v[112:115], v[130:133], v[170:173], v[112:115]
	v_mfma_f32_16x16x32_bf16 v[104:107], v[138:141], v[170:173], v[104:107]
	v_mfma_f32_16x16x32_bf16 v[96:99], v[130:133], v[178:181], v[96:99]
	v_mfma_f32_16x16x32_bf16 v[88:91], v[138:141], v[178:181], v[88:91]
	v_mfma_f32_16x16x32_bf16 v[80:83], v[130:133], v[186:189], v[80:83]
	v_mfma_f32_16x16x32_bf16 v[72:75], v[138:141], v[186:189], v[72:75]
	v_mfma_f32_16x16x32_bf16 v[124:127], v[134:137], v[166:169], v[124:127]
	v_mfma_f32_16x16x32_bf16 v[120:123], v[142:145], v[166:169], v[120:123]
	v_mfma_f32_16x16x32_bf16 v[112:115], v[134:137], v[174:177], v[112:115]
	v_mfma_f32_16x16x32_bf16 v[104:107], v[142:145], v[174:177], v[104:107]
	v_mfma_f32_16x16x32_bf16 v[96:99], v[134:137], v[182:185], v[96:99]
	v_mfma_f32_16x16x32_bf16 v[88:91], v[142:145], v[182:185], v[88:91]
	v_mfma_f32_16x16x32_bf16 v[80:83], v[134:137], v[190:193], v[80:83]
	v_mfma_f32_16x16x32_bf16 v[72:75], v[142:145], v[190:193], v[72:75]
	s_setprio 0
	s_setprio 1
	v_mfma_f32_16x16x32_bf16 v[116:119], v[146:149], v[162:165], v[116:119]
	v_mfma_f32_16x16x32_bf16 v[108:111], v[154:157], v[162:165], v[108:111]
	v_mfma_f32_16x16x32_bf16 v[100:103], v[146:149], v[170:173], v[100:103]
	v_mfma_f32_16x16x32_bf16 v[92:95], v[154:157], v[170:173], v[92:95]
	v_mfma_f32_16x16x32_bf16 v[84:87], v[146:149], v[178:181], v[84:87]
	v_mfma_f32_16x16x32_bf16 v[76:79], v[154:157], v[178:181], v[76:79]
	v_mfma_f32_16x16x32_bf16 v[68:71], v[146:149], v[186:189], v[68:71]
	v_mfma_f32_16x16x32_bf16 v[64:67], v[154:157], v[186:189], v[64:67]
	v_mfma_f32_16x16x32_bf16 v[116:119], v[150:153], v[166:169], v[116:119]
	v_mfma_f32_16x16x32_bf16 v[108:111], v[158:161], v[166:169], v[108:111]
	v_mfma_f32_16x16x32_bf16 v[100:103], v[150:153], v[174:177], v[100:103]
	v_mfma_f32_16x16x32_bf16 v[92:95], v[158:161], v[174:177], v[92:95]
	v_mfma_f32_16x16x32_bf16 v[84:87], v[150:153], v[182:185], v[84:87]
	v_mfma_f32_16x16x32_bf16 v[76:79], v[158:161], v[182:185], v[76:79]
	v_mfma_f32_16x16x32_bf16 v[68:71], v[150:153], v[190:193], v[68:71]
	v_mfma_f32_16x16x32_bf16 v[64:67], v[158:161], v[190:193], v[64:67]
	s_setprio 0
	s_barrier
	s_add_u32 s46, s44, s20
	s_addc_u32 s47, s45, s21
	s_add_i32 m0, s95, 0x18000
	ds_read_b128 v[162:165], v232 offset:49152
	ds_read_b128 v[166:169], v232 offset:50176
	ds_read_b128 v[170:173], v232 offset:51200
	ds_read_b128 v[174:177], v232 offset:52224
	ds_read_b128 v[178:181], v232 offset:53248
	ds_read_b128 v[182:185], v232 offset:54272
	ds_read_b128 v[186:189], v232 offset:55296
	ds_read_b128 v[190:193], v232 offset:56320
	global_load_lds_dwordx4 v200, s[46:47]
	s_add_i32 m0, s95, 0x1a000
	s_nop 0
	global_load_lds_dwordx4 v204, s[46:47]
	s_add_u32 s46, s34, s20
	s_addc_u32 s47, s35, s21
	s_add_i32 m0, s95, 0x1c000
	s_nop 0
	global_load_lds_dwordx4 v200, s[46:47]
	s_add_i32 m0, s95, 0x1e000
	s_nop 0
	global_load_lds_dwordx4 v204, s[46:47]
	s_mov_b32 m0, s30
	s_nop 0
	global_load_lds_dwordx4 v198, s[24:25]
	s_mov_b32 m0, s31
	s_nop 0
	global_load_lds_dwordx4 v202, s[24:25]
	s_add_u32 s10, s10, 0x180
	s_addc_u32 s11, s11, 0
	s_add_u32 s15, s15, 0x100
	s_addc_u32 s16, s16, 0
	s_mov_b32 s17, s22
	s_cmp_ge_u32 s22, s87
	s_cbranch_scc1 .Lg_ctl_done_p
	s_or_b32 s22, s17, 1
	s_lshl_b64 s[34:35], s[22:23], 7
	s_add_i32 s22, s17, 2
	s_lshl_b64 s[28:29], s[22:23], 7
	s_add_i32 s24, s17, 3
	s_mov_b32 s25, s23
	s_lshl_b64 s[24:25], s[24:25], 7
	s_and_b64 vcc, exec, s[84:85]
	s_cbranch_scc1 .Lg_ctl_std_p
	s_add_u32 s34, s10, 0xfffffe80
	s_addc_u32 s35, s11, -1
	s_add_u32 s28, s10, 0xffffff80
	s_addc_u32 s29, s11, -1
	s_mov_b64 s[24:25], s[10:11]

; #define PG8_STAGE(bufoff, gbase, voff) do { _Pragma("unroll") for (int _i = 0; _i < 2; ++_i) \
;         __builtin_amdgcn_global_load_lds((const unsigned*)((const char*)(gbase) + (voff)[_i]), (LAS unsigned*)(lds + (bufoff) + ldsw + _i * 8192), 16, 0, 0); } while (0)
; #define PG8_LDA(dst, b, h) do { _Pragma("unroll") for (int m = 0; m < 4; ++m) _Pragma("unroll") for (int k = 0; k < 2; ++k) dst[m][k] = *(const LAS bf16x8*)(lds + PG8_SA(b, h) + aoff + m * 2048 + k * 1024); } while (0)
; #define PG8_LDB(dst, b, h) do { _Pragma("unroll") for (int n = 0; n < 2; ++n) _Pragma("unroll") for (int k = 0; k < 2; ++k) dst[n][k] = *(const LAS bf16x8*)(lds + PG8_SB(b, h) + boff + n * 2048 + k * 1024); } while (0)
; #define PG8_MMA(ai, bj, At, Bt) do { __builtin_amdgcn_s_setprio(1); _Pragma("unroll") for (int m = 0; m < 4; ++m) _Pragma("unroll") for (int n = 0; n < 2; ++n) _Pragma("unroll") for (int k = 0; k < 2; ++k) \
;         acc[ai][bj][m][n] = __builtin_amdgcn_mfma_f32_16x16x32_bf16(Bt[n][k], At[m][k], acc[ai][bj][m][n], 0, 0, 0); __builtin_amdgcn_s_setprio(0); } while (0)
; #define PG8_WAIT_V(n) asm volatile("s_waitcnt vmcnt(" #n ")" ::: "memory")
; #define PG8_WAIT_L(n) asm volatile("s_waitcnt lgkmcnt(" #n ")" ::: "memory")
; #define PG8_BAR __builtin_amdgcn_s_barrier()
; #define PG8_SCHED __builtin_amdgcn_sched_barrier(0)
; __device__ __forceinline__ void gemm_generic(LAS unsigned char* lds, const GDesc& d, int G, int bx) {
;     ...
;             PG8_LDB(B0, 0, 0); PG8_LDB(B1, 0, 1); PG8_SCHED; PG8_LDA(At, 0, 0); PG8_STAGE(PG8_SA(1, 1), a1 + hstepA, voffA);
;             PG8_WAIT_V(8); PG8_WAIT_L(0); PG8_BAR; PG8_MMA(0, 0, At, B0); PG8_MMA(0, 1, At, B1); PG8_BAR; PG8_SCHED;
;     ...
;             PG8_WAIT_V(8); PG8_WAIT_L(0); PG8_BAR; PG8_MMA(1, 0, At, B0); PG8_MMA(1, 1, At, B1); PG8_BAR; PG8_SCHED;
.Lg_ctl_done_p:
	s_waitcnt vmcnt(8)
	s_waitcnt lgkmcnt(0)
	s_barrier
	s_setprio 1
	v_mfma_f32_16x16x32_bf16 v[60:63], v[130:133], v[162:165], v[60:63]
	v_mfma_f32_16x16x32_bf16 v[56:59], v[138:141], v[162:165], v[56:59]
	v_mfma_f32_16x16x32_bf16 v[48:51], v[130:133], v[170:173], v[48:51]
	v_mfma_f32_16x16x32_bf16 v[40:43], v[138:141], v[170:173], v[40:43]
	v_mfma_f32_16x16x32_bf16 v[32:35], v[130:133], v[178:181], v[32:35]
	v_mfma_f32_16x16x32_bf16 v[24:27], v[138:141], v[178:181], v[24:27]
	v_mfma_f32_16x16x32_bf16 v[16:19], v[130:133], v[186:189], v[16:19]
	v_mfma_f32_16x16x32_bf16 v[8:11], v[138:141], v[186:189], v[8:11]
	v_mfma_f32_16x16x32_bf16 v[60:63], v[134:137], v[166:169], v[60:63]
	v_mfma_f32_16x16x32_bf16 v[56:59], v[142:145], v[166:169], v[56:59]
	v_mfma_f32_16x16x32_bf16 v[48:51], v[134:137], v[174:177], v[48:51]
	v_mfma_f32_16x16x32_bf16 v[40:43], v[142:145], v[174:177], v[40:43]
	v_mfma_f32_16x16x32_bf16 v[32:35], v[134:137], v[182:185], v[32:35]
	v_mfma_f32_16x16x32_bf16 v[24:27], v[142:145], v[182:185], v[24:27]
	v_mfma_f32_16x16x32_bf16 v[16:19], v[134:137], v[190:193], v[16:19]
	v_mfma_f32_16x16x32_bf16 v[8:11], v[142:145], v[190:193], v[8:11]
	s_setprio 0
	s_setprio 1
	v_mfma_f32_16x16x32_bf16 v[52:55], v[146:149], v[162:165], v[52:55]
	v_mfma_f32_16x16x32_bf16 v[44:47], v[154:157], v[162:165], v[44:47]
	v_mfma_f32_16x16x32_bf16 v[36:39], v[146:149], v[170:173], v[36:39]
	v_mfma_f32_16x16x32_bf16 v[28:31], v[154:157], v[170:173], v[28:31]
	v_mfma_f32_16x16x32_bf16 v[20:23], v[146:149], v[178:181], v[20:23]
	v_mfma_f32_16x16x32_bf16 v[12:15], v[154:157], v[178:181], v[12:15]
	v_mfma_f32_16x16x32_bf16 v[4:7], v[146:149], v[186:189], v[4:7]
	v_mfma_f32_16x16x32_bf16 v[0:3], v[154:157], v[186:189], v[0:3]
	v_mfma_f32_16x16x32_bf16 v[52:55], v[150:153], v[166:169], v[52:55]
	v_mfma_f32_16x16x32_bf16 v[44:47], v[158:161], v[166:169], v[44:47]
	v_mfma_f32_16x16x32_bf16 v[36:39], v[150:153], v[174:177], v[36:39]
	v_mfma_f32_16x16x32_bf16 v[28:31], v[158:161], v[174:177], v[28:31]
	v_mfma_f32_16x16x32_bf16 v[20:23], v[150:153], v[182:185], v[20:23]
	v_mfma_f32_16x16x32_bf16 v[12:15], v[158:161], v[182:185], v[12:15]
	v_mfma_f32_16x16x32_bf16 v[4:7], v[150:153], v[190:193], v[4:7]
	v_mfma_f32_16x16x32_bf16 v[0:3], v[158:161], v[190:193], v[0:3]
	s_setprio 0
	s_barrier
	s_cmp_ge_u32 s17, s87
	s_cbranch_scc1 .LBB0_267
.Lg_body:
	ds_read_b128 v[130:133], v250
	ds_read_b128 v[134:137], v250 offset:1024
	ds_read_b128 v[138:141], v250 offset:2048
	ds_read_b128 v[142:145], v250 offset:3072
	ds_read_b128 v[146:149], v251
	ds_read_b128 v[150:153], v251 offset:1024
	ds_read_b128 v[154:157], v251 offset:2048
	ds_read_b128 v[158:161], v251 offset:3072
	s_add_u32 s34, s12, s34
	s_addc_u32 s35, s13, s35
	s_add_i32 m0, s97, 0xc000
	ds_read_b128 v[162:165], v232
	ds_read_b128 v[166:169], v232 offset:1024
	ds_read_b128 v[170:173], v232 offset:2048
	ds_read_b128 v[174:177], v232 offset:3072
	ds_read_b128 v[178:181], v232 offset:4096
	ds_read_b128 v[182:185], v232 offset:5120
	ds_read_b128 v[186:189], v232 offset:6144
	ds_read_b128 v[190:193], v232 offset:7168
	global_load_lds_dwordx4 v198, s[34:35]
	s_add_i32 m0, s97, 0xe000
	s_nop 0
	global_load_lds_dwordx4 v202, s[34:35]
	s_waitcnt vmcnt(8)
	s_waitcnt lgkmcnt(0)
	s_barrier
	s_setprio 1
	v_mfma_f32_16x16x32_bf16 v[124:127], v[130:133], v[162:165], v[124:127]
	v_mfma_f32_16x16x32_bf16 v[120:123], v[138:141], v[162:165], v[120:123]
	v_mfma_f32_16x16x32_bf16 v[112:115], v[130:133], v[170:173], v[112:115]
	v_mfma_f32_16x16x32_bf16 v[104:107], v[138:141], v[170:173], v[104:107]
	v_mfma_f32_16x16x32_bf16 v[96:99], v[130:133], v[178:181], v[96:99]
	v_mfma_f32_16x16x32_bf16 v[88:91], v[138:141], v[178:181], v[88:91]
	v_mfma_f32_16x16x32_bf16 v[80:83], v[130:133], v[186:189], v[80:83]
	v_mfma_f32_16x16x32_bf16 v[72:75], v[138:141], v[186:189], v[72:75]
	v_mfma_f32_16x16x32_bf16 v[124:127], v[134:137], v[166:169], v[124:127]
	v_mfma_f32_16x16x32_bf16 v[120:123], v[142:145], v[166:169], v[120:123]
	v_mfma_f32_16x16x32_bf16 v[112:115], v[134:137], v[174:177], v[112:115]
	v_mfma_f32_16x16x32_bf16 v[104:107], v[142:145], v[174:177], v[104:107]
	v_mfma_f32_16x16x32_bf16 v[96:99], v[134:137], v[182:185], v[96:99]
	v_mfma_f32_16x16x32_bf16 v[88:91], v[142:145], v[182:185], v[88:91]
	v_mfma_f32_16x16x32_bf16 v[80:83], v[134:137], v[190:193], v[80:83]
	v_mfma_f32_16x16x32_bf16 v[72:75], v[142:145], v[190:193], v[72:75]
	s_setprio 0
	s_setprio 1
	v_mfma_f32_16x16x32_bf16 v[116:119], v[146:149], v[162:165], v[116:119]
	v_mfma_f32_16x16x32_bf16 v[108:111], v[154:157], v[162:165], v[108:111]
	v_mfma_f32_16x16x32_bf16 v[100:103], v[146:149], v[170:173], v[100:103]
	v_mfma_f32_16x16x32_bf16 v[92:95], v[154:157], v[170:173], v[92:95]
	v_mfma_f32_16x16x32_bf16 v[84:87], v[146:149], v[178:181], v[84:87]
	v_mfma_f32_16x16x32_bf16 v[76:79], v[154:157], v[178:181], v[76:79]
	v_mfma_f32_16x16x32_bf16 v[68:71], v[146:149], v[186:189], v[68:71]
	v_mfma_f32_16x16x32_bf16 v[64:67], v[154:157], v[186:189], v[64:67]
	v_mfma_f32_16x16x32_bf16 v[116:119], v[150:153], v[166:169], v[116:119]
	v_mfma_f32_16x16x32_bf16 v[108:111], v[158:161], v[166:169], v[108:111]
	v_mfma_f32_16x16x32_bf16 v[100:103], v[150:153], v[174:177], v[100:103]
	v_mfma_f32_16x16x32_bf16 v[92:95], v[158:161], v[174:177], v[92:95]
	v_mfma_f32_16x16x32_bf16 v[84:87], v[150:153], v[182:185], v[84:87]
	v_mfma_f32_16x16x32_bf16 v[76:79], v[158:161], v[182:185], v[76:79]
	v_mfma_f32_16x16x32_bf16 v[68:71], v[150:153], v[190:193], v[68:71]
	v_mfma_f32_16x16x32_bf16 v[64:67], v[158:161], v[190:193], v[64:67]
	s_setprio 0
	s_barrier
; #define PG8_STAGE(bufoff, gbase, voff) do { _Pragma("unroll") for (int _i = 0; _i < 2; ++_i) \
;         __builtin_amdgcn_global_load_lds((const unsigned*)((const char*)(gbase) + (voff)[_i]), (LAS unsigned*)(lds + (bufoff) + ldsw + _i * 8192), 16, 0, 0); } while (0)
; #define PG8_LDA(dst, b, h) do { _Pragma("unroll") for (int m = 0; m < 4; ++m) _Pragma("unroll") for (int k = 0; k < 2; ++k) dst[m][k] = *(const LAS bf16x8*)(lds + PG8_SA(b, h) + aoff + m * 2048 + k * 1024); } while (0)
; #define PG8_LDB(dst, b, h) do { _Pragma("unroll") for (int n = 0; n < 2; ++n) _Pragma("unroll") for (int k = 0; k < 2; ++k) dst[n][k] = *(const LAS bf16x8*)(lds + PG8_SB(b, h) + boff + n * 2048 + k * 1024); } while (0)
; #define PG8_MMA(ai, bj, At, Bt) do { __builtin_amdgcn_s_setprio(1); _Pragma("unroll") for (int m = 0; m < 4; ++m) _Pragma("unroll") for (int n = 0; n < 2; ++n) _Pragma("unroll") for (int k = 0; k < 2; ++k) \
;         acc[ai][bj][m][n] = __builtin_amdgcn_mfma_f32_16x16x32_bf16(Bt[n][k], At[m][k], acc[ai][bj][m][n], 0, 0, 0); __builtin_amdgcn_s_setprio(0); } while (0)
; #define PG8_WAIT_V(n) asm volatile("s_waitcnt vmcnt(" #n ")" ::: "memory")
; #define PG8_WAIT_L(n) asm volatile("s_waitcnt lgkmcnt(" #n ")" ::: "memory")
; #define PG8_BAR __builtin_amdgcn_s_barrier()
; #define PG8_SCHED __builtin_amdgcn_sched_barrier(0)
; __device__ __forceinline__ void gemm_generic(LAS unsigned char* lds, const GDesc& d, int G, int bx) {
;     ...
;             PG8_LDA(At, 0, 1); PG8_STAGE(PG8_SB(0, 0), b2, voffB); PG8_STAGE(PG8_SB(0, 1), b2 + hstepB, voffB); PG8_STAGE(PG8_SA(0, 0), a2, voffA);
;             PG8_WAIT_V(8); PG8_WAIT_L(0); PG8_BAR; PG8_MMA(1, 0, At, B0); PG8_MMA(1, 1, At, B1); PG8_BAR; PG8_SCHED;
;             PG8_LDB(B0, 1, 0); PG8_LDB(B1, 1, 1); PG8_SCHED; PG8_LDA(At, 1, 0); PG8_STAGE(PG8_SA(0, 1), a2 + hstepA, voffA);
	s_add_i32 m0, s95, 0x10000
	ds_read_b128 v[162:165], v232 offset:16384
	ds_read_b128 v[166:169], v232 offset:17408
	ds_read_b128 v[170:173], v232 offset:18432
	ds_read_b128 v[174:177], v232 offset:19456
	ds_read_b128 v[178:181], v232 offset:20480
	ds_read_b128 v[182:185], v232 offset:21504
	ds_read_b128 v[186:189], v232 offset:22528
	ds_read_b128 v[190:193], v232 offset:23552
	global_load_lds_dwordx4 v200, s[44:45]
	s_add_i32 m0, s95, 0x12000
	s_add_u32 s34, s44, s76
	s_addc_u32 s35, s45, s77
	global_load_lds_dwordx4 v204, s[44:45]
	s_add_i32 m0, s95, 0x14000
	s_nop 0
	global_load_lds_dwordx4 v200, s[34:35]
	s_add_i32 m0, s95, 0x16000
	s_nop 0
	global_load_lds_dwordx4 v204, s[34:35]
	s_mov_b32 m0, s97
	s_nop 0
	global_load_lds_dwordx4 v198, s[28:29]
	s_mov_b32 m0, s27
	s_nop 0
	global_load_lds_dwordx4 v202, s[28:29]
	s_waitcnt vmcnt(8)
	s_waitcnt lgkmcnt(0)
	s_barrier
	s_setprio 1
	v_mfma_f32_16x16x32_bf16 v[60:63], v[130:133], v[162:165], v[60:63]
	v_mfma_f32_16x16x32_bf16 v[56:59], v[138:141], v[162:165], v[56:59]
	v_mfma_f32_16x16x32_bf16 v[48:51], v[130:133], v[170:173], v[48:51]
	v_mfma_f32_16x16x32_bf16 v[40:43], v[138:141], v[170:173], v[40:43]
	v_mfma_f32_16x16x32_bf16 v[32:35], v[130:133], v[178:181], v[32:35]
	v_mfma_f32_16x16x32_bf16 v[24:27], v[138:141], v[178:181], v[24:27]
	v_mfma_f32_16x16x32_bf16 v[16:19], v[130:133], v[186:189], v[16:19]
	v_mfma_f32_16x16x32_bf16 v[8:11], v[138:141], v[186:189], v[8:11]
	v_mfma_f32_16x16x32_bf16 v[60:63], v[134:137], v[166:169], v[60:63]
	v_mfma_f32_16x16x32_bf16 v[56:59], v[142:145], v[166:169], v[56:59]
	v_mfma_f32_16x16x32_bf16 v[48:51], v[134:137], v[174:177], v[48:51]
	v_mfma_f32_16x16x32_bf16 v[40:43], v[142:145], v[174:177], v[40:43]
	v_mfma_f32_16x16x32_bf16 v[32:35], v[134:137], v[182:185], v[32:35]
	v_mfma_f32_16x16x32_bf16 v[24:27], v[142:145], v[182:185], v[24:27]
	v_mfma_f32_16x16x32_bf16 v[16:19], v[134:137], v[190:193], v[16:19]
	v_mfma_f32_16x16x32_bf16 v[8:11], v[142:145], v[190:193], v[8:11]
	s_setprio 0
	s_setprio 1
	v_mfma_f32_16x16x32_bf16 v[52:55], v[146:149], v[162:165], v[52:55]
	v_mfma_f32_16x16x32_bf16 v[44:47], v[154:157], v[162:165], v[44:47]
	v_mfma_f32_16x16x32_bf16 v[36:39], v[146:149], v[170:173], v[36:39]
	v_mfma_f32_16x16x32_bf16 v[28:31], v[154:157], v[170:173], v[28:31]
	v_mfma_f32_16x16x32_bf16 v[20:23], v[146:149], v[178:181], v[20:23]
	v_mfma_f32_16x16x32_bf16 v[12:15], v[154:157], v[178:181], v[12:15]
	v_mfma_f32_16x16x32_bf16 v[4:7], v[146:149], v[186:189], v[4:7]
	v_mfma_f32_16x16x32_bf16 v[0:3], v[154:157], v[186:189], v[0:3]
	v_mfma_f32_16x16x32_bf16 v[52:55], v[150:153], v[166:169], v[52:55]
	v_mfma_f32_16x16x32_bf16 v[44:47], v[158:161], v[166:169], v[44:47]
	v_mfma_f32_16x16x32_bf16 v[36:39], v[150:153], v[174:177], v[36:39]
	v_mfma_f32_16x16x32_bf16 v[28:31], v[158:161], v[174:177], v[28:31]
	v_mfma_f32_16x16x32_bf16 v[20:23], v[150:153], v[182:185], v[20:23]
	v_mfma_f32_16x16x32_bf16 v[12:15], v[158:161], v[182:185], v[12:15]
	v_mfma_f32_16x16x32_bf16 v[4:7], v[150:153], v[190:193], v[4:7]
	v_mfma_f32_16x16x32_bf16 v[0:3], v[158:161], v[190:193], v[0:3]
	s_setprio 0
	s_barrier
	s_add_i32 s26, 0, 0x1c000
	ds_read_b128 v[130:133], v252
	ds_read_b128 v[134:137], v252 offset:1024
	ds_read_b128 v[138:141], v252 offset:2048
	ds_read_b128 v[142:145], v252 offset:3072
	ds_read_b128 v[146:149], v253
	ds_read_b128 v[150:153], v253 offset:1024
	ds_read_b128 v[154:157], v253 offset:2048
	ds_read_b128 v[158:161], v253 offset:3072
	s_add_u32 s28, s28, s74
	s_addc_u32 s29, s29, s75
	s_mov_b32 m0, s64
	ds_read_b128 v[162:165], v232 offset:32768
	ds_read_b128 v[166:169], v232 offset:33792
	ds_read_b128 v[170:173], v232 offset:34816
	ds_read_b128 v[174:177], v232 offset:35840
	ds_read_b128 v[178:181], v232 offset:36864
	ds_read_b128 v[182:185], v232 offset:37888
	ds_read_b128 v[186:189], v232 offset:38912
	ds_read_b128 v[190:193], v232 offset:39936
	global_load_lds_dwordx4 v198, s[28:29]
	s_mov_b32 m0, s65
	s_nop 0
	global_load_lds_dwordx4 v202, s[28:29]
	s_waitcnt vmcnt(8)
	s_waitcnt lgkmcnt(0)
	s_barrier
; #define PG8_STAGE(bufoff, gbase, voff) do { _Pragma("unroll") for (int _i = 0; _i < 2; ++_i) \
;         __builtin_amdgcn_global_load_lds((const unsigned*)((const char*)(gbase) + (voff)[_i]), (LAS unsigned*)(lds + (bufoff) + ldsw + _i * 8192), 16, 0, 0); } while (0)
; #define PG8_LDA(dst, b, h) do { _Pragma("unroll") for (int m = 0; m < 4; ++m) _Pragma("unroll") for (int k = 0; k < 2; ++k) dst[m][k] = *(const LAS bf16x8*)(lds + PG8_SA(b, h) + aoff + m * 2048 + k * 1024); } while (0)
; #define PG8_MMA(ai, bj, At, Bt) do { __builtin_amdgcn_s_setprio(1); _Pragma("unroll") for (int m = 0; m < 4; ++m) _Pragma("unroll") for (int n = 0; n < 2; ++n) _Pragma("unroll") for (int k = 0; k < 2; ++k) \
;         acc[ai][bj][m][n] = __builtin_amdgcn_mfma_f32_16x16x32_bf16(Bt[n][k], At[m][k], acc[ai][bj][m][n], 0, 0, 0); __builtin_amdgcn_s_setprio(0); } while (0)
; #define PG8_WAIT_V(n) asm volatile("s_waitcnt vmcnt(" #n ")" ::: "memory")
; #define PG8_WAIT_L(n) asm volatile("s_waitcnt lgkmcnt(" #n ")" ::: "memory")
; #define PG8_BAR __builtin_amdgcn_s_barrier()
; #define PG8_SCHED __builtin_amdgcn_sched_barrier(0)
; __device__ __forceinline__ void gemm_generic(LAS unsigned char* lds, const GDesc& d, int G, int bx) {
;     ...
;             const char* a1 = cA + a_koff(d, t + 1);
;             const char* a2 = last ? nA : cA + a_koff(d, t + 2); const char* b2 = last ? nB : cB + (size_t)(t + 2) * kstep;
;             const char* a3 = last ? nA + a_koff(d, 1) : cA + a_koff(d, t + 3); const char* b3 = b2 + kstep;
;     ...
;             PG8_WAIT_V(8); PG8_WAIT_L(0); PG8_BAR; PG8_MMA(0, 0, At, B0); PG8_MMA(0, 1, At, B1); PG8_BAR; PG8_SCHED;
;             PG8_LDA(At, 1, 1); PG8_STAGE(PG8_SB(1, 0), b3, voffB); PG8_STAGE(PG8_SB(1, 1), b3 + hstepB, voffB); PG8_STAGE(PG8_SA(1, 0), a3, voffA);
	s_setprio 1
	v_mfma_f32_16x16x32_bf16 v[124:127], v[130:133], v[162:165], v[124:127]
	v_mfma_f32_16x16x32_bf16 v[120:123], v[138:141], v[162:165], v[120:123]
	v_mfma_f32_16x16x32_bf16 v[112:115], v[130:133], v[170:173], v[112:115]
	v_mfma_f32_16x16x32_bf16 v[104:107], v[138:141], v[170:173], v[104:107]
	v_mfma_f32_16x16x32_bf16 v[96:99], v[130:133], v[178:181], v[96:99]
	v_mfma_f32_16x16x32_bf16 v[88:91], v[138:141], v[178:181], v[88:91]
	v_mfma_f32_16x16x32_bf16 v[80:83], v[130:133], v[186:189], v[80:83]
	v_mfma_f32_16x16x32_bf16 v[72:75], v[138:141], v[186:189], v[72:75]
	v_mfma_f32_16x16x32_bf16 v[124:127], v[134:137], v[166:169], v[124:127]
	v_mfma_f32_16x16x32_bf16 v[120:123], v[142:145], v[166:169], v[120:123]
	v_mfma_f32_16x16x32_bf16 v[112:115], v[134:137], v[174:177], v[112:115]
	v_mfma_f32_16x16x32_bf16 v[104:107], v[142:145], v[174:177], v[104:107]
	v_mfma_f32_16x16x32_bf16 v[96:99], v[134:137], v[182:185], v[96:99]
	v_mfma_f32_16x16x32_bf16 v[88:91], v[142:145], v[182:185], v[88:91]
	v_mfma_f32_16x16x32_bf16 v[80:83], v[134:137], v[190:193], v[80:83]
	v_mfma_f32_16x16x32_bf16 v[72:75], v[142:145], v[190:193], v[72:75]
	s_setprio 0
	s_setprio 1
	v_mfma_f32_16x16x32_bf16 v[116:119], v[146:149], v[162:165], v[116:119]
	v_mfma_f32_16x16x32_bf16 v[108:111], v[154:157], v[162:165], v[108:111]
	v_mfma_f32_16x16x32_bf16 v[100:103], v[146:149], v[170:173], v[100:103]
	v_mfma_f32_16x16x32_bf16 v[92:95], v[154:157], v[170:173], v[92:95]
	v_mfma_f32_16x16x32_bf16 v[84:87], v[146:149], v[178:181], v[84:87]
	v_mfma_f32_16x16x32_bf16 v[76:79], v[154:157], v[178:181], v[76:79]
	v_mfma_f32_16x16x32_bf16 v[68:71], v[146:149], v[186:189], v[68:71]
	v_mfma_f32_16x16x32_bf16 v[64:67], v[154:157], v[186:189], v[64:67]
	v_mfma_f32_16x16x32_bf16 v[116:119], v[150:153], v[166:169], v[116:119]
	v_mfma_f32_16x16x32_bf16 v[108:111], v[158:161], v[166:169], v[108:111]
	v_mfma_f32_16x16x32_bf16 v[100:103], v[150:153], v[174:177], v[100:103]
	v_mfma_f32_16x16x32_bf16 v[92:95], v[158:161], v[174:177], v[92:95]
	v_mfma_f32_16x16x32_bf16 v[84:87], v[150:153], v[182:185], v[84:87]
	v_mfma_f32_16x16x32_bf16 v[76:79], v[158:161], v[182:185], v[76:79]
	v_mfma_f32_16x16x32_bf16 v[68:71], v[150:153], v[190:193], v[68:71]
	v_mfma_f32_16x16x32_bf16 v[64:67], v[158:161], v[190:193], v[64:67]
	s_setprio 0
	s_barrier
	s_add_u32 s46, s44, s20
	s_addc_u32 s47, s45, s21
	s_add_i32 m0, s95, 0x18000
	ds_read_b128 v[162:165], v232 offset:49152
	ds_read_b128 v[166:169], v232 offset:50176
	ds_read_b128 v[170:173], v232 offset:51200
	ds_read_b128 v[174:177], v232 offset:52224
	ds_read_b128 v[178:181], v232 offset:53248
	ds_read_b128 v[182:185], v232 offset:54272
	ds_read_b128 v[186:189], v232 offset:55296
	ds_read_b128 v[190:193], v232 offset:56320
	global_load_lds_dwordx4 v200, s[46:47]
	s_add_i32 m0, s95, 0x1a000
	s_nop 0
	global_load_lds_dwordx4 v204, s[46:47]
	s_add_u32 s46, s34, s20
	s_addc_u32 s47, s35, s21
	s_add_i32 m0, s95, 0x1c000
	s_nop 0
	global_load_lds_dwordx4 v200, s[46:47]
	s_add_i32 m0, s95, 0x1e000
	s_nop 0
	global_load_lds_dwordx4 v204, s[46:47]
	s_mov_b32 m0, s30
	s_nop 0
	global_load_lds_dwordx4 v198, s[24:25]
	s_mov_b32 m0, s31
	s_nop 0
	global_load_lds_dwordx4 v202, s[24:25]
	s_add_u32 s10, s10, 0x180
	s_addc_u32 s11, s11, 0
	s_add_u32 s15, s15, 0x100
	s_addc_u32 s16, s16, 0
	s_mov_b32 s17, s22
	s_cmp_ge_u32 s22, s87
	s_cbranch_scc1 .Lg_ctl_done
	s_or_b32 s22, s17, 1
	s_lshl_b64 s[34:35], s[22:23], 7
	s_add_i32 s22, s17, 2
	s_lshl_b64 s[28:29], s[22:23], 7
	s_add_i32 s24, s17, 3
	s_mov_b32 s25, s23
	s_lshl_b64 s[24:25], s[24:25], 7
	s_and_b64 vcc, exec, s[84:85]
	s_cbranch_scc1 .Lg_ctl_std
	s_add_u32 s34, s10, 0xfffffe80
	s_addc_u32 s35, s11, -1
	s_add_u32 s28, s10, 0xffffff80
	s_addc_u32 s29, s11, -1
	s_mov_b64 s[24:25], s[10:11]

; #define PG8_MMA(ai, bj, At, Bt) do { __builtin_amdgcn_s_setprio(1); _Pragma("unroll") for (int m = 0; m < 4; ++m) _Pragma("unroll") for (int n = 0; n < 2; ++n) _Pragma("unroll") for (int k = 0; k < 2; ++k) \
;         acc[ai][bj][m][n] = __builtin_amdgcn_mfma_f32_16x16x32_bf16(Bt[n][k], At[m][k], acc[ai][bj][m][n], 0, 0, 0); __builtin_amdgcn_s_setprio(0); } while (0)
; #define PG8_WAIT_V(n) asm volatile("s_waitcnt vmcnt(" #n ")" ::: "memory")
; #define PG8_WAIT_L(n) asm volatile("s_waitcnt lgkmcnt(" #n ")" ::: "memory")
; #define PG8_BAR __builtin_amdgcn_s_barrier()
; #define PG8_SCHED __builtin_amdgcn_sched_barrier(0)
; __device__ __forceinline__ void gemm_generic(LAS unsigned char* lds, const GDesc& d, int G, int bx) {
;     ...
;             PG8_WAIT_V(8); PG8_WAIT_L(0); PG8_BAR; PG8_MMA(1, 0, At, B0); PG8_MMA(1, 1, At, B1); PG8_BAR; PG8_SCHED;
;         }
.Lg_ctl_done:
	s_waitcnt vmcnt(8)
	s_waitcnt lgkmcnt(0)
	s_barrier
	s_setprio 1
	v_mfma_f32_16x16x32_bf16 v[60:63], v[130:133], v[162:165], v[60:63]
	v_mfma_f32_16x16x32_bf16 v[56:59], v[138:141], v[162:165], v[56:59]
	v_mfma_f32_16x16x32_bf16 v[48:51], v[130:133], v[170:173], v[48:51]
	v_mfma_f32_16x16x32_bf16 v[40:43], v[138:141], v[170:173], v[40:43]
	v_mfma_f32_16x16x32_bf16 v[32:35], v[130:133], v[178:181], v[32:35]
	v_mfma_f32_16x16x32_bf16 v[24:27], v[138:141], v[178:181], v[24:27]
	v_mfma_f32_16x16x32_bf16 v[16:19], v[130:133], v[186:189], v[16:19]
	v_mfma_f32_16x16x32_bf16 v[8:11], v[138:141], v[186:189], v[8:11]
	v_mfma_f32_16x16x32_bf16 v[60:63], v[134:137], v[166:169], v[60:63]
	v_mfma_f32_16x16x32_bf16 v[56:59], v[142:145], v[166:169], v[56:59]
	v_mfma_f32_16x16x32_bf16 v[48:51], v[134:137], v[174:177], v[48:51]
	v_mfma_f32_16x16x32_bf16 v[40:43], v[142:145], v[174:177], v[40:43]
	v_mfma_f32_16x16x32_bf16 v[32:35], v[134:137], v[182:185], v[32:35]
	v_mfma_f32_16x16x32_bf16 v[24:27], v[142:145], v[182:185], v[24:27]
	v_mfma_f32_16x16x32_bf16 v[16:19], v[134:137], v[190:193], v[16:19]
	v_mfma_f32_16x16x32_bf16 v[8:11], v[142:145], v[190:193], v[8:11]
	s_setprio 0
	s_setprio 1
	v_mfma_f32_16x16x32_bf16 v[52:55], v[146:149], v[162:165], v[52:55]
	v_mfma_f32_16x16x32_bf16 v[44:47], v[154:157], v[162:165], v[44:47]
	v_mfma_f32_16x16x32_bf16 v[36:39], v[146:149], v[170:173], v[36:39]
	v_mfma_f32_16x16x32_bf16 v[28:31], v[154:157], v[170:173], v[28:31]
	v_mfma_f32_16x16x32_bf16 v[20:23], v[146:149], v[178:181], v[20:23]
	v_mfma_f32_16x16x32_bf16 v[12:15], v[154:157], v[178:181], v[12:15]
	v_mfma_f32_16x16x32_bf16 v[4:7], v[146:149], v[186:189], v[4:7]
	v_mfma_f32_16x16x32_bf16 v[0:3], v[154:157], v[186:189], v[0:3]
	v_mfma_f32_16x16x32_bf16 v[52:55], v[150:153], v[166:169], v[52:55]
	v_mfma_f32_16x16x32_bf16 v[44:47], v[158:161], v[166:169], v[44:47]
	v_mfma_f32_16x16x32_bf16 v[36:39], v[150:153], v[174:177], v[36:39]
	v_mfma_f32_16x16x32_bf16 v[28:31], v[158:161], v[174:177], v[28:31]
	v_mfma_f32_16x16x32_bf16 v[20:23], v[150:153], v[182:185], v[20:23]
	v_mfma_f32_16x16x32_bf16 v[12:15], v[158:161], v[182:185], v[12:15]
	v_mfma_f32_16x16x32_bf16 v[4:7], v[150:153], v[190:193], v[4:7]
	v_mfma_f32_16x16x32_bf16 v[0:3], v[158:161], v[190:193], v[0:3]
	s_setprio 0
	s_barrier
	s_cmp_ge_u32 s17, s87
	s_cbranch_scc0 .Lg_body
	s_branch .LBB0_267
	s_nop 0
	s_nop 0
	s_nop 0
	s_nop 0
	s_nop 0
	s_nop 0
	s_nop 0
